# scan3 wave-0 triangular-inverse chain kept in registers: accumulator tiles packed to bf16 (v_cvt_pk) feed the next MFMA directly, same k-permutation on both operands, no LDS round trips (bf16 MFMA f32
# speedup vs baseline: 1.0805x; 1.0145x over previous
; __device__ __forceinline__ int mrow(int r, int hi) { return (r & 3) + 8 * (r >> 2) + 4 * hi; }
; template <int NV, bool WITHY> __device__ __forceinline__ void scan_chunk(const ScanLds& L, f32x16& st, bool hasT, int kt, int vt, int wave, int lane_, bf16* ypark = nullptr) {
;     ...
;     if (wave == 0) {
;         __builtin_amdgcn_s_setprio(3);
; #pragma unroll
;         for (int r = 0; r < 16; ++r) { Q[r] = 0.f; QT[r] = 0.f; }
;         mm32<4>(Q, L.Bt, 72, 0, L.Kap, 72, 0, l31, hi);
;         mm32<4>(QT, L.Kap, 72, 0, L.Bt, 72, 0, l31, hi);
; #pragma unroll
;         for (int r = 0; r < 16; ++r) { const int row = mrow(r, hi); Q[r] = row < l31 ? Q[r] : 0.f; QT[r] = l31 < row ? QT[r] : 0.f; W[r] = (row == l31 ? 1.f : 0.f) - QT[r]; }
;         nat_store(L.BQ, Q, l31, hi); nat_store(L.BQT, QT, l31, hi);
;         {   f32x16 Qn, QTn;
; #pragma unroll
;             for (int r = 0; r < 16; ++r) { Qn[r] = 0.f; QTn[r] = 0.f; }
;             mm32<2>(Qn, L.BQT, 40, 0, L.BQ, 40, 0, l31, hi); mm32<2>(QTn, L.BQ, 40, 0, L.BQT, 40, 0, l31, hi); Q = Qn; QT = QTn; }
.Lw0skip2:
	s_waitcnt vmcnt(21)
	s_setprio 3
	v_add3_u32 v19, s57, v222, v217
	ds_read_b128 v[20:23], v19
	ds_read_b128 v[24:27], v19 offset:32
	ds_read_b128 v[28:31], v223
	ds_read_b128 v[66:69], v223 offset:32
	ds_read_b128 v[70:73], v19 offset:64
	ds_read_b128 v[74:77], v223 offset:64
	ds_read_b128 v[78:81], v19 offset:96
	ds_read_b128 v[224:227], v223 offset:96
	v_lshlrev_b32_e32 v19, 2, v214
	s_waitcnt lgkmcnt(5)
	v_mfma_f32_32x32x16_bf16 v[50:65], v[28:31], v[20:23], 0
	v_cmp_lt_i32_e64 s[54:55], v213, v19
	v_cmp_lt_i32_e32 vcc, v19, v213
	v_add_u32_e32 v33, 24, v19
	v_add_u32_e32 v32, 25, v19
	v_mfma_f32_32x32x16_bf16 v[34:49], v[20:23], v[28:31], 0
	v_or_b32_e32 v23, 2, v19
	v_or_b32_e32 v22, 3, v19
	v_add_u32_e32 v29, 16, v19
	v_add_u32_e32 v28, 17, v19
	v_add_u32_e32 v31, 18, v19
	v_add_u32_e32 v30, 19, v19
	s_waitcnt lgkmcnt(4)
	v_mfma_f32_32x32x16_bf16 v[50:65], v[66:69], v[24:27], v[50:65]
	v_mfma_f32_32x32x16_bf16 v[34:49], v[24:27], v[66:69], v[34:49]
	v_add_u32_e32 v25, 8, v19
	v_add_u32_e32 v24, 9, v19
	v_add_u32_e32 v27, 10, v19
	v_add_u32_e32 v26, 11, v19
	s_waitcnt lgkmcnt(2)
	v_mfma_f32_32x32x16_bf16 v[50:65], v[74:77], v[70:73], v[50:65]
	v_mfma_f32_32x32x16_bf16 v[34:49], v[70:73], v[74:77], v[34:49]
	s_waitcnt lgkmcnt(0)
	v_mfma_f32_32x32x16_bf16 v[50:65], v[224:227], v[78:81], v[50:65]
	v_mfma_f32_32x32x16_bf16 v[34:49], v[78:81], v[224:227], v[34:49]
	s_nop 10
	v_cndmask_b32_e64 v67, 0, v50, s[54:55]
	v_cmp_eq_u32_e64 s[54:55], v19, v213
	v_cndmask_b32_e64 v68, v51, 0, vcc
	s_nop 0
	v_cndmask_b32_e64 v20, 0, 1.0, s[54:55]
	v_cndmask_b32_e32 v66, 0, v34, vcc
	v_sub_f32_e32 v34, v20, v67
	v_or_b32_e32 v20, 1, v19
	v_cmp_eq_u32_e32 vcc, v20, v213
	v_cmp_lt_i32_e64 s[54:55], v20, v213
	s_nop 0
	v_cndmask_b32_e64 v20, 0, 1.0, vcc
	v_cmp_lt_i32_e32 vcc, v23, v213
	v_cndmask_b32_e64 v50, 0, v35, s[54:55]
	v_sub_f32_e32 v35, v20, v68
	v_cndmask_b32_e32 v51, 0, v36, vcc
	v_cmp_lt_i32_e32 vcc, v213, v23
	v_cmp_lt_i32_e64 s[54:55], v213, v22
	v_cvt_pk_bf16_f32 v50, v66, v50
	v_cndmask_b32_e32 v20, 0, v52, vcc
	v_cmp_lt_i32_e32 vcc, v22, v213
	v_cndmask_b32_e64 v21, 0, v53, s[54:55]
	v_cmp_eq_u32_e64 s[54:55], v22, v213
	v_cndmask_b32_e32 v52, 0, v37, vcc
	v_cmp_eq_u32_e32 vcc, v23, v213
	v_cndmask_b32_e64 v23, 0, 1.0, s[54:55]
	v_cmp_lt_i32_e64 s[54:55], v213, v24
	v_cndmask_b32_e64 v22, 0, 1.0, vcc
	v_cmp_lt_i32_e32 vcc, v25, v213
	v_pk_add_f32 v[36:37], v[22:23], v[20:21] neg_lo:[0,1] neg_hi:[0,1]
	v_cndmask_b32_e64 v23, 0, v55, s[54:55]
	v_cndmask_b32_e32 v53, 0, v38, vcc
	v_cmp_lt_i32_e32 vcc, v213, v25
	v_cmp_eq_u32_e64 s[54:55], v24, v213
	v_cvt_pk_bf16_f32 v51, v51, v52
	v_cndmask_b32_e32 v22, 0, v54, vcc
	v_cmp_lt_i32_e32 vcc, v24, v213
	v_mov_b64_e32 v[246:247], v[50:51]
	s_nop 0
	v_cndmask_b32_e32 v54, 0, v39, vcc
	v_cmp_eq_u32_e32 vcc, v25, v213
	v_cndmask_b32_e64 v25, 0, 1.0, s[54:55]
	v_cmp_lt_i32_e64 s[54:55], v213, v26
	v_cndmask_b32_e64 v24, 0, 1.0, vcc
	v_cmp_lt_i32_e32 vcc, v27, v213
	v_pk_add_f32 v[38:39], v[24:25], v[22:23] neg_lo:[0,1] neg_hi:[0,1]
	v_cndmask_b32_e64 v25, 0, v57, s[54:55]
	v_cndmask_b32_e32 v55, 0, v40, vcc
	v_cmp_lt_i32_e32 vcc, v213, v27
	v_cmp_eq_u32_e64 s[54:55], v26, v213
	v_cvt_pk_bf16_f32 v50, v53, v54
	v_cndmask_b32_e32 v24, 0, v56, vcc
	v_cmp_lt_i32_e32 vcc, v26, v213
	s_nop 1
	v_cndmask_b32_e32 v56, 0, v41, vcc
	v_cmp_eq_u32_e32 vcc, v27, v213
	v_cndmask_b32_e64 v27, 0, 1.0, s[54:55]
	v_cmp_lt_i32_e64 s[54:55], v213, v28
	v_cndmask_b32_e64 v26, 0, 1.0, vcc
	v_cmp_lt_i32_e32 vcc, v29, v213
	v_pk_add_f32 v[40:41], v[26:27], v[24:25] neg_lo:[0,1] neg_hi:[0,1]
	v_cndmask_b32_e64 v27, 0, v59, s[54:55]
	v_cndmask_b32_e32 v57, 0, v42, vcc
	v_cmp_lt_i32_e32 vcc, v213, v29
	v_cmp_eq_u32_e64 s[54:55], v28, v213
	v_cvt_pk_bf16_f32 v51, v55, v56
	v_cndmask_b32_e32 v26, 0, v58, vcc
	v_cmp_lt_i32_e32 vcc, v28, v213
	v_mov_b64_e32 v[248:249], v[50:51]
	s_nop 0
	v_cndmask_b32_e32 v58, 0, v43, vcc
	v_cmp_eq_u32_e32 vcc, v29, v213
	v_cndmask_b32_e64 v29, 0, 1.0, s[54:55]
	v_cmp_lt_i32_e64 s[54:55], v213, v30
	v_cndmask_b32_e64 v28, 0, 1.0, vcc
	v_cmp_lt_i32_e32 vcc, v31, v213
	v_pk_add_f32 v[42:43], v[28:29], v[26:27] neg_lo:[0,1] neg_hi:[0,1]
	v_cndmask_b32_e64 v29, 0, v61, s[54:55]
	v_cndmask_b32_e32 v59, 0, v44, vcc
	v_cmp_lt_i32_e32 vcc, v213, v31
	v_cmp_eq_u32_e64 s[54:55], v30, v213
	v_cvt_pk_bf16_f32 v50, v57, v58
	v_cndmask_b32_e32 v28, 0, v60, vcc
	v_cmp_lt_i32_e32 vcc, v30, v213
	s_nop 1
	v_cndmask_b32_e32 v60, 0, v45, vcc
	v_cmp_eq_u32_e32 vcc, v31, v213
	v_cndmask_b32_e64 v31, 0, 1.0, s[54:55]
	v_cmp_lt_i32_e64 s[54:55], v213, v32
	v_cndmask_b32_e64 v30, 0, 1.0, vcc
	v_cmp_lt_i32_e32 vcc, v33, v213
	v_pk_add_f32 v[44:45], v[30:31], v[28:29] neg_lo:[0,1] neg_hi:[0,1]
	v_cndmask_b32_e64 v31, 0, v63, s[54:55]
	v_cndmask_b32_e32 v61, 0, v46, vcc
	v_cmp_lt_i32_e32 vcc, v213, v33
	v_add_u32_e32 v63, 27, v19
	v_add_u32_e32 v19, 26, v19
	v_cndmask_b32_e32 v30, 0, v62, vcc
	v_cmp_lt_i32_e32 vcc, v32, v213
	v_cmp_eq_u32_e64 s[54:55], v32, v213
	v_cvt_pk_bf16_f32 v51, v59, v60
	v_cndmask_b32_e32 v62, 0, v47, vcc
	v_cmp_eq_u32_e32 vcc, v33, v213
	v_cndmask_b32_e64 v33, 0, 1.0, s[54:55]
	v_mov_b64_e32 v[250:251], v[50:51]
	v_cndmask_b32_e64 v32, 0, 1.0, vcc
	v_cmp_lt_i32_e32 vcc, v19, v213
	v_pk_add_f32 v[46:47], v[32:33], v[30:31] neg_lo:[0,1] neg_hi:[0,1]
	v_cvt_pk_bf16_f32 v50, v61, v62
	v_cndmask_b32_e32 v69, 0, v48, vcc
	v_cmp_lt_i32_e32 vcc, v213, v19
	v_cmp_lt_i32_e64 s[54:55], v213, v63
	s_nop 0
	v_cndmask_b32_e32 v32, 0, v64, vcc
	v_cmp_lt_i32_e32 vcc, v63, v213
	v_cndmask_b32_e64 v33, 0, v65, s[54:55]
	v_cmp_eq_u32_e64 s[54:55], v63, v213
	v_cndmask_b32_e32 v64, 0, v49, vcc
	v_cvt_pk_bf16_f32 v51, v69, v64
	v_mov_b64_e32 v[252:253], v[50:51]
	v_cvt_pk_bf16_f32 v51, v20, v21
	v_cvt_pk_bf16_f32 v4, v22, v23
	v_cvt_pk_bf16_f32 v5, v24, v25
	v_cvt_pk_bf16_f32 v20, v26, v27
	v_cvt_pk_bf16_f32 v21, v28, v29
	v_cmp_eq_u32_e32 vcc, v19, v213
	v_cvt_pk_bf16_f32 v50, v67, v68
	v_mov_b64_e32 v[6:7], v[20:21]
	v_cvt_pk_bf16_f32 v20, v30, v31
	v_cvt_pk_bf16_f32 v21, v32, v33
	v_cndmask_b32_e64 v49, 0, 1.0, s[54:55]
	v_cndmask_b32_e64 v48, 0, 1.0, vcc
	v_mov_b64_e32 v[2:3], v[50:51]
	v_mov_b64_e32 v[8:9], v[20:21]
	v_add_u32_e32 v19, v221, v215
	v_pk_add_f32 v[48:49], v[48:49], v[32:33] neg_lo:[0,1] neg_hi:[0,1]
	v_add_u32_e32 v32, v220, v215
	s_waitcnt lgkmcnt(1)
; template <int NV, bool WITHY> __device__ __forceinline__ void scan_chunk(const ScanLds& L, f32x16& st, bool hasT, int kt, int vt, int wave, int lane_, bf16* ypark = nullptr) {
;     ...
;         {   f32x16 Qn, QTn;
; #pragma unroll
;             for (int r = 0; r < 16; ++r) { Qn[r] = 0.f; QTn[r] = 0.f; }
;             mm32<2>(Qn, L.BQT, 40, 0, L.BQ, 40, 0, l31, hi); mm32<2>(QTn, L.BQ, 40, 0, L.BQT, 40, 0, l31, hi); Q = Qn; QT = QTn; }
; #pragma unroll
;         for (int n = 1; n < 3; ++n) {
;             nat_store(L.BQ, Q, l31, hi); nat_store(L.BQT, QT, l31, hi); nat_store(L.BW, W, l31, hi);
;             f32x16 Qn, QTn;
; #pragma unroll
;             for (int r = 0; r < 16; ++r) { Qn[r] = 0.f; QTn[r] = 0.f; }
;             mm32<2>(W, L.BQ, 40, 0, L.BW, 40, 0, l31, hi); mm32<2>(Qn, L.BQT, 40, 0, L.BQ, 40, 0, l31, hi); mm32<2>(QTn, L.BQ, 40, 0, L.BQT, 40, 0, l31, hi); Q = Qn; QT = QTn; }
	v_mfma_f32_32x32x16_bf16 v[50:65], v[2:5], v[246:249], 0
	v_add_u32_e32 v33, v219, v215
	v_mfma_f32_32x32x16_bf16 v[66:81], v[246:249], v[2:5], 0
	s_waitcnt lgkmcnt(0)
	v_mfma_f32_32x32x16_bf16 v[50:65], v[6:9], v[250:253], v[50:65]
	v_mfma_f32_32x32x16_bf16 v[66:81], v[250:253], v[6:9], v[66:81]
	s_nop 10
	v_cvt_pk_bf16_f32 v246, v50, v51
	v_cvt_pk_bf16_f32 v247, v52, v53
	v_cvt_pk_bf16_f32 v248, v54, v55
	v_cvt_pk_bf16_f32 v249, v56, v57
	v_cvt_pk_bf16_f32 v250, v58, v59
	v_cvt_pk_bf16_f32 v251, v60, v61
	v_cvt_pk_bf16_f32 v252, v62, v63
	v_cvt_pk_bf16_f32 v253, v64, v65
	v_cvt_pk_bf16_f32 v2, v66, v67
	v_cvt_pk_bf16_f32 v3, v68, v69
	v_cvt_pk_bf16_f32 v4, v70, v71
	v_cvt_pk_bf16_f32 v5, v72, v73
	v_cvt_pk_bf16_f32 v6, v74, v75
	v_cvt_pk_bf16_f32 v7, v76, v77
	v_cvt_pk_bf16_f32 v8, v78, v79
	v_cvt_pk_bf16_f32 v9, v80, v81
	v_cvt_pk_bf16_f32 v10, v34, v35
	v_cvt_pk_bf16_f32 v11, v36, v37
	v_cvt_pk_bf16_f32 v12, v38, v39
	v_cvt_pk_bf16_f32 v13, v40, v41
	v_cvt_pk_bf16_f32 v14, v42, v43
	v_cvt_pk_bf16_f32 v15, v44, v45
	v_cvt_pk_bf16_f32 v16, v46, v47
	v_cvt_pk_bf16_f32 v17, v48, v49
	s_waitcnt lgkmcnt(1)
	v_mfma_f32_32x32x16_bf16 v[34:49], v[246:249], v[10:13], v[34:49]
	s_waitcnt lgkmcnt(1)
	v_mfma_f32_32x32x16_bf16 v[66:81], v[2:5], v[246:249], 0
	v_mfma_f32_32x32x16_bf16 v[34:49], v[250:253], v[14:17], v[34:49]
	v_mfma_f32_32x32x16_bf16 v[50:65], v[246:249], v[2:5], 0
	s_waitcnt lgkmcnt(0)
	v_mfma_f32_32x32x16_bf16 v[66:81], v[6:9], v[250:253], v[66:81]
	v_mfma_f32_32x32x16_bf16 v[50:65], v[250:253], v[6:9], v[50:65]
	s_nop 10
	v_cvt_pk_bf16_f32 v246, v66, v67
	v_cvt_pk_bf16_f32 v247, v68, v69
	v_cvt_pk_bf16_f32 v248, v70, v71
	v_cvt_pk_bf16_f32 v249, v72, v73
	v_cvt_pk_bf16_f32 v250, v74, v75
	v_cvt_pk_bf16_f32 v251, v76, v77
	v_cvt_pk_bf16_f32 v252, v78, v79
	v_cvt_pk_bf16_f32 v253, v80, v81
	v_cvt_pk_bf16_f32 v2, v50, v51
	v_cvt_pk_bf16_f32 v3, v52, v53
	v_cvt_pk_bf16_f32 v4, v54, v55
	v_cvt_pk_bf16_f32 v5, v56, v57
	v_cvt_pk_bf16_f32 v6, v58, v59
	v_cvt_pk_bf16_f32 v7, v60, v61
	v_cvt_pk_bf16_f32 v8, v62, v63
	v_cvt_pk_bf16_f32 v9, v64, v65
	v_cvt_pk_bf16_f32 v10, v34, v35
	v_cvt_pk_bf16_f32 v11, v36, v37
	v_cvt_pk_bf16_f32 v12, v38, v39
	v_cvt_pk_bf16_f32 v13, v40, v41
	v_cvt_pk_bf16_f32 v14, v42, v43
	v_cvt_pk_bf16_f32 v15, v44, v45
	v_cvt_pk_bf16_f32 v16, v46, v47
	v_cvt_pk_bf16_f32 v17, v48, v49
	s_waitcnt lgkmcnt(1)
	v_mfma_f32_32x32x16_bf16 v[34:49], v[246:249], v[10:13], v[34:49]
	s_waitcnt lgkmcnt(2)
	v_mfma_f32_32x32x16_bf16 v[34:49], v[250:253], v[14:17], v[34:49]
	s_waitcnt lgkmcnt(1)
	v_mfma_f32_32x32x16_bf16 v[66:81], v[2:5], v[246:249], 0
	v_mfma_f32_32x32x16_bf16 v[50:65], v[246:249], v[2:5], 0
	s_waitcnt lgkmcnt(0)
	v_mfma_f32_32x32x16_bf16 v[66:81], v[6:9], v[250:253], v[66:81]
	v_mfma_f32_32x32x16_bf16 v[50:65], v[250:253], v[6:9], v[50:65]

; __device__ __forceinline__ unsigned f2bf(float f) { return pk2(f, f) & 0xffffu; }
; __device__ __forceinline__ int mrow(int r, int hi) { return (r & 3) + 8 * (r >> 2) + 4 * hi; }
; template <int NV, bool WITHY> __device__ __forceinline__ void scan_chunk(const ScanLds& L, f32x16& st, bool hasT, int kt, int vt, int wave, int lane_, bf16* ypark = nullptr) {
;     ...
;     if (wave == 0) {
; #pragma unroll
;         for (int n = 3; n < 5; ++n) {
;             nat_store(L.BQ, Q, l31, hi); if (n < 4) nat_store(L.BQT, QT, l31, hi); nat_store(L.BW, W, l31, hi);
;             f32x16 Qn, QTn;
; #pragma unroll
;             for (int r = 0; r < 16; ++r) { Qn[r] = 0.f; QTn[r] = 0.f; }
;             mm32<2>(W, L.BQ, 40, 0, L.BW, 40, 0, l31, hi);
;             if (n < 4) { mm32<2>(Qn, L.BQT, 40, 0, L.BQ, 40, 0, l31, hi); mm32<2>(QTn, L.BQ, 40, 0, L.BQT, 40, 0, l31, hi); Q = Qn; QT = QTn; } }
; #pragma unroll
;         for (int r = 0; r < 16; ++r) L.TiT[mrow(r, hi) * 40 + l31] = (bf16)f2bf(W[r]);
;         __builtin_amdgcn_s_setprio(0);
;     }
.LBB0_747:
	s_andn2_b64 vcc, exec, s[26:27]
	s_cbranch_vccnz .LBB0_749
	v_cvt_pk_bf16_f32 v50, v50, v51
	v_cvt_pk_bf16_f32 v51, v52, v53
	v_cvt_pk_bf16_f32 v52, v54, v55
	v_cvt_pk_bf16_f32 v53, v56, v57
	v_mov_b64_e32 v[246:247], v[50:51]
	v_mov_b64_e32 v[248:249], v[52:53]
	v_cvt_pk_bf16_f32 v50, v58, v59
	v_cvt_pk_bf16_f32 v51, v60, v61
	v_cvt_pk_bf16_f32 v52, v62, v63
	v_cvt_pk_bf16_f32 v53, v64, v65
	v_cvt_pk_bf16_f32 v66, v66, v67
	v_cvt_pk_bf16_f32 v67, v68, v69
	v_mov_b64_e32 v[250:251], v[50:51]
	v_mov_b64_e32 v[252:253], v[52:53]
	v_cvt_pk_bf16_f32 v50, v34, v35
	v_cvt_pk_bf16_f32 v51, v36, v37
	v_mov_b64_e32 v[2:3], v[66:67]
	v_cvt_pk_bf16_f32 v66, v70, v71
	v_cvt_pk_bf16_f32 v67, v72, v73
	v_mov_b64_e32 v[10:11], v[50:51]
	v_cvt_pk_bf16_f32 v50, v38, v39
	v_cvt_pk_bf16_f32 v51, v40, v41
	v_mov_b64_e32 v[4:5], v[66:67]
	v_cvt_pk_bf16_f32 v66, v74, v75
	v_cvt_pk_bf16_f32 v67, v76, v77
	v_mov_b64_e32 v[12:13], v[50:51]
	v_cvt_pk_bf16_f32 v50, v42, v43
	v_cvt_pk_bf16_f32 v51, v44, v45
	v_mov_b64_e32 v[6:7], v[66:67]
	v_cvt_pk_bf16_f32 v66, v78, v79
	v_cvt_pk_bf16_f32 v67, v80, v81
	v_mov_b64_e32 v[14:15], v[50:51]
	v_cvt_pk_bf16_f32 v50, v46, v47
	v_cvt_pk_bf16_f32 v51, v48, v49
	v_mov_b64_e32 v[8:9], v[66:67]
	v_mov_b64_e32 v[16:17], v[50:51]
	v_add_u32_e32 v74, v220, v215
	v_add_u32_e32 v75, v219, v215
	s_waitcnt lgkmcnt(2)
	v_mfma_f32_32x32x16_bf16 v[34:49], v[2:5], v[10:13], v[34:49]
	s_waitcnt lgkmcnt(0)
	v_mfma_f32_32x32x16_bf16 v[34:49], v[6:9], v[14:17], v[34:49]
	v_add_u32_e32 v58, v221, v215
	s_waitcnt lgkmcnt(1)
	v_mfma_f32_32x32x16_bf16 v[50:65], v[246:249], v[2:5], 0
	s_waitcnt lgkmcnt(0)
	v_mfma_f32_32x32x16_bf16 v[50:65], v[250:253], v[6:9], v[50:65]
	s_nop 11
	v_cvt_pk_bf16_f32 v2, v50, v51
	v_cvt_pk_bf16_f32 v3, v52, v53
	v_cvt_pk_bf16_f32 v4, v54, v55
	v_cvt_pk_bf16_f32 v5, v56, v57
	v_cvt_pk_bf16_f32 v6, v58, v59
	v_cvt_pk_bf16_f32 v7, v60, v61
	v_cvt_pk_bf16_f32 v8, v62, v63
	v_cvt_pk_bf16_f32 v9, v64, v65
	v_cvt_pk_bf16_f32 v10, v34, v35
	v_cvt_pk_bf16_f32 v11, v36, v37
	v_cvt_pk_bf16_f32 v12, v38, v39
	v_cvt_pk_bf16_f32 v13, v40, v41
	v_cvt_pk_bf16_f32 v14, v42, v43
	v_cvt_pk_bf16_f32 v15, v44, v45
	v_cvt_pk_bf16_f32 v16, v46, v47
	v_cvt_pk_bf16_f32 v17, v48, v49
	s_waitcnt lgkmcnt(2)
	v_mfma_f32_32x32x16_bf16 v[34:49], v[2:5], v[10:13], v[34:49]
	v_lshlrev_b32_e32 v50, 1, v213
	s_waitcnt lgkmcnt(0)
	v_mfma_f32_32x32x16_bf16 v[34:49], v[6:9], v[14:17], v[34:49]
	s_nop 11
	v_cvt_pk_bf16_f32 v34, v34, s0
	s_movk_i32 s0, 0x140
	v_mul_lo_u32 v51, v214, s0
	v_add3_u32 v50, s35, v50, v51
	ds_write_b16 v50, v34
	v_cvt_pk_bf16_f32 v34, v35, s0
	ds_write_b16 v50, v34 offset:80
	v_cvt_pk_bf16_f32 v34, v36, s0
	ds_write_b16 v50, v34 offset:160
	v_cvt_pk_bf16_f32 v34, v37, s0
	ds_write_b16 v50, v34 offset:240
	v_cvt_pk_bf16_f32 v34, v38, s0
	ds_write_b16 v50, v34 offset:640
	v_cvt_pk_bf16_f32 v34, v39, s0
	ds_write_b16 v50, v34 offset:720
	v_cvt_pk_bf16_f32 v34, v40, s0
	ds_write_b16 v50, v34 offset:800
	v_cvt_pk_bf16_f32 v34, v41, s0
	ds_write_b16 v50, v34 offset:880
	v_cvt_pk_bf16_f32 v34, v42, s0
	ds_write_b16 v50, v34 offset:1280
	v_cvt_pk_bf16_f32 v34, v43, s0
	ds_write_b16 v50, v34 offset:1360
	v_cvt_pk_bf16_f32 v34, v44, s0
	ds_write_b16 v50, v34 offset:1440
	v_cvt_pk_bf16_f32 v34, v45, s0
	ds_write_b16 v50, v34 offset:1520
	v_cvt_pk_bf16_f32 v34, v46, s0
	ds_write_b16 v50, v34 offset:1920
	v_cvt_pk_bf16_f32 v34, v47, s0
	ds_write_b16 v50, v34 offset:2000
	v_cvt_pk_bf16_f32 v34, v48, s0
	ds_write_b16 v50, v34 offset:2080
	v_cvt_pk_bf16_f32 v34, v49, s0
	ds_write_b16 v50, v34 offset:2160
	s_setprio 0

; __device__ __forceinline__ int mrow(int r, int hi) { return (r & 3) + 8 * (r >> 2) + 4 * hi; }
; template <int NV, bool WITHY> __device__ __forceinline__ void scan_chunk(const ScanLds& L, f32x16& st, bool hasT, int kt, int vt, int wave, int lane_, bf16* ypark = nullptr) {
;     ...
;     if (wave == 0) {
;         __builtin_amdgcn_s_setprio(3);
; #pragma unroll
;         for (int r = 0; r < 16; ++r) { Q[r] = 0.f; QT[r] = 0.f; }
;         mm32<4>(Q, L.Bt, 72, 0, L.Kap, 72, 0, l31, hi);
;         mm32<4>(QT, L.Kap, 72, 0, L.Bt, 72, 0, l31, hi);
; #pragma unroll
;         for (int r = 0; r < 16; ++r) { const int row = mrow(r, hi); Q[r] = row < l31 ? Q[r] : 0.f; QT[r] = l31 < row ? QT[r] : 0.f; W[r] = (row == l31 ? 1.f : 0.f) - QT[r]; }
;         nat_store(L.BQ, Q, l31, hi); nat_store(L.BQT, QT, l31, hi);
;         {   f32x16 Qn, QTn;
; #pragma unroll
;             for (int r = 0; r < 16; ++r) { Qn[r] = 0.f; QTn[r] = 0.f; }
;             mm32<2>(Qn, L.BQT, 40, 0, L.BQ, 40, 0, l31, hi); mm32<2>(QTn, L.BQ, 40, 0, L.BQT, 40, 0, l31, hi); Q = Qn; QT = QTn; }
.Lw0skip3:
	s_waitcnt vmcnt(21)
	s_setprio 3
	v_add3_u32 v19, s57, v176, v211
	ds_read_b128 v[20:23], v19
	ds_read_b128 v[24:27], v19 offset:32
	ds_read_b128 v[28:31], v177
	ds_read_b128 v[66:69], v177 offset:32
	ds_read_b128 v[70:73], v19 offset:64
	ds_read_b128 v[74:77], v177 offset:64
	ds_read_b128 v[78:81], v19 offset:96
	ds_read_b128 v[212:215], v177 offset:96
	v_cmp_lt_i32_e64 s[54:55], v99, v174
	s_waitcnt lgkmcnt(5)
	v_mfma_f32_32x32x16_bf16 v[50:65], v[28:31], v[20:23], 0
	v_cmp_lt_i32_e32 vcc, v174, v99
	v_add_u32_e32 v33, 24, v174
	v_add_u32_e32 v32, 25, v174
	v_mfma_f32_32x32x16_bf16 v[34:49], v[20:23], v[28:31], 0
	v_add_u32_e32 v29, 16, v174
	v_add_u32_e32 v28, 17, v174
	v_add_u32_e32 v31, 18, v174
	v_add_u32_e32 v30, 19, v174
	s_waitcnt lgkmcnt(4)
	v_mfma_f32_32x32x16_bf16 v[50:65], v[66:69], v[24:27], v[50:65]
	v_mfma_f32_32x32x16_bf16 v[34:49], v[24:27], v[66:69], v[34:49]
	v_add_u32_e32 v25, 8, v174
	v_add_u32_e32 v24, 9, v174
	v_add_u32_e32 v27, 10, v174
	v_add_u32_e32 v26, 11, v174
	v_add_u32_e32 v68, 26, v174
	s_waitcnt lgkmcnt(2)
	v_mfma_f32_32x32x16_bf16 v[50:65], v[74:77], v[70:73], v[50:65]
	v_mfma_f32_32x32x16_bf16 v[34:49], v[70:73], v[74:77], v[34:49]
	s_waitcnt lgkmcnt(0)
	v_mfma_f32_32x32x16_bf16 v[50:65], v[212:215], v[78:81], v[50:65]
	v_mfma_f32_32x32x16_bf16 v[34:49], v[78:81], v[212:215], v[34:49]
	s_nop 10
	v_cndmask_b32_e64 v66, 0, v50, s[54:55]
	v_cmp_eq_u32_e64 s[54:55], v174, v99
	v_cndmask_b32_e64 v67, v51, 0, vcc
	s_nop 0
	v_cndmask_b32_e64 v20, 0, 1.0, s[54:55]
	v_cmp_lt_i32_e64 s[54:55], v172, v99
	v_cndmask_b32_e32 v19, 0, v34, vcc
	v_cmp_eq_u32_e32 vcc, v172, v99
	v_sub_f32_e32 v34, v20, v66
	v_cndmask_b32_e64 v50, 0, v35, s[54:55]
	v_cndmask_b32_e64 v20, 0, 1.0, vcc
	v_cmp_lt_i32_e32 vcc, v170, v99
	v_sub_f32_e32 v35, v20, v67
	v_cmp_lt_i32_e64 s[54:55], v99, v168
	v_cndmask_b32_e32 v51, 0, v36, vcc
	v_cmp_lt_i32_e32 vcc, v99, v170
	v_cndmask_b32_e64 v21, 0, v53, s[54:55]
	v_cmp_eq_u32_e64 s[54:55], v168, v99
	v_cndmask_b32_e32 v20, 0, v52, vcc
	v_cmp_lt_i32_e32 vcc, v168, v99
	v_cndmask_b32_e64 v23, 0, 1.0, s[54:55]
	v_cmp_lt_i32_e64 s[54:55], v99, v24
	v_cndmask_b32_e32 v52, 0, v37, vcc
	v_cmp_eq_u32_e32 vcc, v170, v99
	v_cvt_pk_bf16_f32 v50, v19, v50
	v_cvt_pk_bf16_f32 v51, v51, v52
	v_cndmask_b32_e64 v22, 0, 1.0, vcc
	v_cmp_lt_i32_e32 vcc, v25, v99
	v_pk_add_f32 v[36:37], v[22:23], v[20:21] neg_lo:[0,1] neg_hi:[0,1]
	v_cndmask_b32_e64 v23, 0, v55, s[54:55]
	v_cndmask_b32_e32 v53, 0, v38, vcc
	v_cmp_lt_i32_e32 vcc, v99, v25
	v_cmp_eq_u32_e64 s[54:55], v24, v99
	v_mov_b64_e32 v[246:247], v[50:51]
	v_cndmask_b32_e32 v22, 0, v54, vcc
	v_cmp_lt_i32_e32 vcc, v24, v99
	v_add_u32_e32 v19, v175, v1
	s_nop 0
	v_cndmask_b32_e32 v54, 0, v39, vcc
	v_cmp_eq_u32_e32 vcc, v25, v99
	v_cndmask_b32_e64 v25, 0, 1.0, s[54:55]
	v_cmp_lt_i32_e64 s[54:55], v99, v26
	v_cndmask_b32_e64 v24, 0, 1.0, vcc
	v_cmp_lt_i32_e32 vcc, v27, v99
	v_pk_add_f32 v[38:39], v[24:25], v[22:23] neg_lo:[0,1] neg_hi:[0,1]
	v_cndmask_b32_e64 v25, 0, v57, s[54:55]
	v_cndmask_b32_e32 v55, 0, v40, vcc
	v_cmp_lt_i32_e32 vcc, v99, v27
	v_cmp_eq_u32_e64 s[54:55], v26, v99
	v_cvt_pk_bf16_f32 v50, v53, v54
	v_cndmask_b32_e32 v24, 0, v56, vcc
	v_cmp_lt_i32_e32 vcc, v26, v99
	s_nop 1
	v_cndmask_b32_e32 v56, 0, v41, vcc
	v_cmp_eq_u32_e32 vcc, v27, v99
	v_cndmask_b32_e64 v27, 0, 1.0, s[54:55]
	v_cmp_lt_i32_e64 s[54:55], v99, v28
	v_cndmask_b32_e64 v26, 0, 1.0, vcc
	v_cmp_lt_i32_e32 vcc, v29, v99
	v_pk_add_f32 v[40:41], v[26:27], v[24:25] neg_lo:[0,1] neg_hi:[0,1]
	v_cndmask_b32_e64 v27, 0, v59, s[54:55]
	v_cndmask_b32_e32 v57, 0, v42, vcc
	v_cmp_lt_i32_e32 vcc, v99, v29
	v_cmp_eq_u32_e64 s[54:55], v28, v99
	v_cvt_pk_bf16_f32 v51, v55, v56
	v_cndmask_b32_e32 v26, 0, v58, vcc
	v_cmp_lt_i32_e32 vcc, v28, v99
	v_mov_b64_e32 v[248:249], v[50:51]
	s_nop 0
	v_cndmask_b32_e32 v58, 0, v43, vcc
	v_cmp_eq_u32_e32 vcc, v29, v99
	v_cndmask_b32_e64 v29, 0, 1.0, s[54:55]
	v_cmp_lt_i32_e64 s[54:55], v99, v30
	v_cndmask_b32_e64 v28, 0, 1.0, vcc
	v_cmp_lt_i32_e32 vcc, v31, v99
	v_pk_add_f32 v[42:43], v[28:29], v[26:27] neg_lo:[0,1] neg_hi:[0,1]
	v_cndmask_b32_e64 v29, 0, v61, s[54:55]
	v_cndmask_b32_e32 v59, 0, v44, vcc
	v_cmp_lt_i32_e32 vcc, v99, v31
	v_cmp_eq_u32_e64 s[54:55], v30, v99
	v_cvt_pk_bf16_f32 v50, v57, v58
	v_cndmask_b32_e32 v28, 0, v60, vcc
	v_cmp_lt_i32_e32 vcc, v30, v99
	s_nop 1
	v_cndmask_b32_e32 v60, 0, v45, vcc
	v_cmp_eq_u32_e32 vcc, v31, v99
	v_cndmask_b32_e64 v31, 0, 1.0, s[54:55]
	v_cmp_lt_i32_e64 s[54:55], v99, v32
	v_cndmask_b32_e64 v30, 0, 1.0, vcc
	v_cmp_lt_i32_e32 vcc, v33, v99
	v_pk_add_f32 v[44:45], v[30:31], v[28:29] neg_lo:[0,1] neg_hi:[0,1]
	v_cndmask_b32_e64 v31, 0, v63, s[54:55]
	v_cndmask_b32_e32 v61, 0, v46, vcc
	v_cmp_lt_i32_e32 vcc, v99, v33
	v_cmp_eq_u32_e64 s[54:55], v32, v99
	v_add_u32_e32 v63, 27, v174
	v_cndmask_b32_e32 v30, 0, v62, vcc
	v_cmp_lt_i32_e32 vcc, v32, v99
	v_cvt_pk_bf16_f32 v51, v59, v60
	v_mov_b64_e32 v[250:251], v[50:51]
	v_cndmask_b32_e32 v62, 0, v47, vcc
	v_cmp_eq_u32_e32 vcc, v33, v99
	v_cndmask_b32_e64 v33, 0, 1.0, s[54:55]
	v_cvt_pk_bf16_f32 v50, v61, v62
	v_cndmask_b32_e64 v32, 0, 1.0, vcc
	v_cmp_lt_i32_e32 vcc, v68, v99
	v_pk_add_f32 v[46:47], v[32:33], v[30:31] neg_lo:[0,1] neg_hi:[0,1]
	v_cmp_lt_i32_e64 s[54:55], v99, v63
	v_cndmask_b32_e32 v69, 0, v48, vcc
	v_cmp_lt_i32_e32 vcc, v99, v68
	v_cndmask_b32_e64 v33, 0, v65, s[54:55]
	v_cmp_eq_u32_e64 s[54:55], v63, v99
	v_cndmask_b32_e32 v32, 0, v64, vcc
	v_cmp_lt_i32_e32 vcc, v63, v99
	s_nop 1
	v_cndmask_b32_e32 v64, 0, v49, vcc
	v_cvt_pk_bf16_f32 v51, v69, v64
	v_mov_b64_e32 v[252:253], v[50:51]
	v_cvt_pk_bf16_f32 v51, v20, v21
	v_cvt_pk_bf16_f32 v4, v22, v23
	v_cvt_pk_bf16_f32 v5, v24, v25
	v_cvt_pk_bf16_f32 v20, v26, v27
	v_cvt_pk_bf16_f32 v21, v28, v29
	v_cmp_eq_u32_e32 vcc, v68, v99
	v_cvt_pk_bf16_f32 v50, v66, v67
	v_mov_b64_e32 v[6:7], v[20:21]
	v_cvt_pk_bf16_f32 v20, v30, v31
	v_cvt_pk_bf16_f32 v21, v32, v33
	v_cndmask_b32_e64 v49, 0, 1.0, s[54:55]
	v_cndmask_b32_e64 v48, 0, 1.0, vcc
	v_mov_b64_e32 v[2:3], v[50:51]
	v_mov_b64_e32 v[8:9], v[20:21]
	v_pk_add_f32 v[48:49], v[48:49], v[32:33] neg_lo:[0,1] neg_hi:[0,1]
	v_add_u32_e32 v32, v173, v1
	s_waitcnt lgkmcnt(1)
; template <int NV, bool WITHY> __device__ __forceinline__ void scan_chunk(const ScanLds& L, f32x16& st, bool hasT, int kt, int vt, int wave, int lane_, bf16* ypark = nullptr) {
;     ...
; #pragma unroll
;         for (int n = 1; n < 3; ++n) {
;             nat_store(L.BQ, Q, l31, hi); nat_store(L.BQT, QT, l31, hi); nat_store(L.BW, W, l31, hi);
;             f32x16 Qn, QTn;
; #pragma unroll
;             for (int r = 0; r < 16; ++r) { Qn[r] = 0.f; QTn[r] = 0.f; }
;             mm32<2>(W, L.BQ, 40, 0, L.BW, 40, 0, l31, hi); mm32<2>(Qn, L.BQT, 40, 0, L.BQ, 40, 0, l31, hi); mm32<2>(QTn, L.BQ, 40, 0, L.BQT, 40, 0, l31, hi); Q = Qn; QT = QTn; }
	v_mfma_f32_32x32x16_bf16 v[50:65], v[2:5], v[246:249], 0
	v_add_u32_e32 v33, v171, v1
	v_mfma_f32_32x32x16_bf16 v[66:81], v[246:249], v[2:5], 0
	s_waitcnt lgkmcnt(0)
	v_mfma_f32_32x32x16_bf16 v[50:65], v[6:9], v[250:253], v[50:65]
	v_mfma_f32_32x32x16_bf16 v[66:81], v[250:253], v[6:9], v[66:81]
	s_nop 10
	v_cvt_pk_bf16_f32 v246, v50, v51
	v_cvt_pk_bf16_f32 v247, v52, v53
	v_cvt_pk_bf16_f32 v248, v54, v55
	v_cvt_pk_bf16_f32 v249, v56, v57
	v_cvt_pk_bf16_f32 v250, v58, v59
	v_cvt_pk_bf16_f32 v251, v60, v61
	v_cvt_pk_bf16_f32 v252, v62, v63
	v_cvt_pk_bf16_f32 v253, v64, v65
	v_cvt_pk_bf16_f32 v2, v66, v67
	v_cvt_pk_bf16_f32 v3, v68, v69
	v_cvt_pk_bf16_f32 v4, v70, v71
	v_cvt_pk_bf16_f32 v5, v72, v73
	v_cvt_pk_bf16_f32 v6, v74, v75
	v_cvt_pk_bf16_f32 v7, v76, v77
	v_cvt_pk_bf16_f32 v8, v78, v79
	v_cvt_pk_bf16_f32 v9, v80, v81
	v_cvt_pk_bf16_f32 v10, v34, v35
	v_cvt_pk_bf16_f32 v11, v36, v37
	v_cvt_pk_bf16_f32 v12, v38, v39
	v_cvt_pk_bf16_f32 v13, v40, v41
	v_cvt_pk_bf16_f32 v14, v42, v43
	v_cvt_pk_bf16_f32 v15, v44, v45
	v_cvt_pk_bf16_f32 v16, v46, v47
	v_cvt_pk_bf16_f32 v17, v48, v49
	s_waitcnt lgkmcnt(1)
	v_mfma_f32_32x32x16_bf16 v[34:49], v[246:249], v[10:13], v[34:49]
	s_waitcnt lgkmcnt(1)
	v_mfma_f32_32x32x16_bf16 v[66:81], v[2:5], v[246:249], 0
	v_mfma_f32_32x32x16_bf16 v[34:49], v[250:253], v[14:17], v[34:49]
	v_mfma_f32_32x32x16_bf16 v[50:65], v[246:249], v[2:5], 0
	s_waitcnt lgkmcnt(0)
	v_mfma_f32_32x32x16_bf16 v[66:81], v[6:9], v[250:253], v[66:81]
	v_mfma_f32_32x32x16_bf16 v[50:65], v[250:253], v[6:9], v[50:65]
	s_nop 10
	v_cvt_pk_bf16_f32 v246, v66, v67
	v_cvt_pk_bf16_f32 v247, v68, v69
	v_cvt_pk_bf16_f32 v248, v70, v71
	v_cvt_pk_bf16_f32 v249, v72, v73
	v_cvt_pk_bf16_f32 v250, v74, v75
	v_cvt_pk_bf16_f32 v251, v76, v77
	v_cvt_pk_bf16_f32 v252, v78, v79
	v_cvt_pk_bf16_f32 v253, v80, v81
	v_cvt_pk_bf16_f32 v2, v50, v51
	v_cvt_pk_bf16_f32 v3, v52, v53
	v_cvt_pk_bf16_f32 v4, v54, v55
	v_cvt_pk_bf16_f32 v5, v56, v57
	v_cvt_pk_bf16_f32 v6, v58, v59
	v_cvt_pk_bf16_f32 v7, v60, v61
	v_cvt_pk_bf16_f32 v8, v62, v63
	v_cvt_pk_bf16_f32 v9, v64, v65
	v_cvt_pk_bf16_f32 v10, v34, v35
	v_cvt_pk_bf16_f32 v11, v36, v37
	v_cvt_pk_bf16_f32 v12, v38, v39
	v_cvt_pk_bf16_f32 v13, v40, v41
	v_cvt_pk_bf16_f32 v14, v42, v43
	v_cvt_pk_bf16_f32 v15, v44, v45
	v_cvt_pk_bf16_f32 v16, v46, v47
	v_cvt_pk_bf16_f32 v17, v48, v49
	s_waitcnt lgkmcnt(1)
	v_mfma_f32_32x32x16_bf16 v[34:49], v[246:249], v[10:13], v[34:49]
	s_waitcnt lgkmcnt(2)
	v_mfma_f32_32x32x16_bf16 v[34:49], v[250:253], v[14:17], v[34:49]
	s_waitcnt lgkmcnt(1)
	v_mfma_f32_32x32x16_bf16 v[66:81], v[2:5], v[246:249], 0
	v_mfma_f32_32x32x16_bf16 v[50:65], v[246:249], v[2:5], 0
	s_waitcnt lgkmcnt(0)
	v_mfma_f32_32x32x16_bf16 v[66:81], v[6:9], v[250:253], v[66:81]
	v_mfma_f32_32x32x16_bf16 v[50:65], v[250:253], v[6:9], v[50:65]

; __device__ __forceinline__ unsigned f2bf(float f) { return pk2(f, f) & 0xffffu; }
; __device__ __forceinline__ int mrow(int r, int hi) { return (r & 3) + 8 * (r >> 2) + 4 * hi; }
; template <int NV, bool WITHY> __device__ __forceinline__ void scan_chunk(const ScanLds& L, f32x16& st, bool hasT, int kt, int vt, int wave, int lane_, bf16* ypark = nullptr) {
;     ...
;     if (wave == 0) {
; #pragma unroll
;         for (int n = 3; n < 5; ++n) {
;             nat_store(L.BQ, Q, l31, hi); if (n < 4) nat_store(L.BQT, QT, l31, hi); nat_store(L.BW, W, l31, hi);
;             f32x16 Qn, QTn;
; #pragma unroll
;             for (int r = 0; r < 16; ++r) { Qn[r] = 0.f; QTn[r] = 0.f; }
;             mm32<2>(W, L.BQ, 40, 0, L.BW, 40, 0, l31, hi);
;             if (n < 4) { mm32<2>(Qn, L.BQT, 40, 0, L.BQ, 40, 0, l31, hi); mm32<2>(QTn, L.BQ, 40, 0, L.BQT, 40, 0, l31, hi); Q = Qn; QT = QTn; } }
; #pragma unroll
;         for (int r = 0; r < 16; ++r) L.TiT[mrow(r, hi) * 40 + l31] = (bf16)f2bf(W[r]);
;         __builtin_amdgcn_s_setprio(0);
.LBB0_787:
	v_cvt_pk_bf16_f32 v50, v50, v51
	v_cvt_pk_bf16_f32 v51, v52, v53
	v_cvt_pk_bf16_f32 v52, v54, v55
	v_cvt_pk_bf16_f32 v53, v56, v57
	v_mov_b64_e32 v[246:247], v[50:51]
	v_mov_b64_e32 v[248:249], v[52:53]
	v_cvt_pk_bf16_f32 v50, v58, v59
	v_cvt_pk_bf16_f32 v51, v60, v61
	v_cvt_pk_bf16_f32 v52, v62, v63
	v_cvt_pk_bf16_f32 v53, v64, v65
	v_cvt_pk_bf16_f32 v66, v66, v67
	v_cvt_pk_bf16_f32 v67, v68, v69
	v_mov_b64_e32 v[250:251], v[50:51]
	v_mov_b64_e32 v[252:253], v[52:53]
	v_cvt_pk_bf16_f32 v50, v34, v35
	v_cvt_pk_bf16_f32 v51, v36, v37
	v_mov_b64_e32 v[2:3], v[66:67]
	v_cvt_pk_bf16_f32 v66, v70, v71
	v_cvt_pk_bf16_f32 v67, v72, v73
	v_mov_b64_e32 v[10:11], v[50:51]
	v_cvt_pk_bf16_f32 v50, v38, v39
	v_cvt_pk_bf16_f32 v51, v40, v41
	v_mov_b64_e32 v[4:5], v[66:67]
	v_cvt_pk_bf16_f32 v66, v74, v75
	v_cvt_pk_bf16_f32 v67, v76, v77
	v_mov_b64_e32 v[12:13], v[50:51]
	v_cvt_pk_bf16_f32 v50, v42, v43
	v_cvt_pk_bf16_f32 v51, v44, v45
	v_mov_b64_e32 v[6:7], v[66:67]
	v_cvt_pk_bf16_f32 v66, v78, v79
	v_cvt_pk_bf16_f32 v67, v80, v81
	v_mov_b64_e32 v[14:15], v[50:51]
	v_cvt_pk_bf16_f32 v50, v46, v47
	v_cvt_pk_bf16_f32 v51, v48, v49
	v_mov_b64_e32 v[8:9], v[66:67]
	v_mov_b64_e32 v[16:17], v[50:51]
	v_add_u32_e32 v74, v173, v1
	v_add_u32_e32 v75, v171, v1
	s_waitcnt lgkmcnt(2)
	v_mfma_f32_32x32x16_bf16 v[34:49], v[2:5], v[10:13], v[34:49]
	s_waitcnt lgkmcnt(0)
	v_mfma_f32_32x32x16_bf16 v[34:49], v[6:9], v[14:17], v[34:49]
	v_add_u32_e32 v58, v175, v1
	s_waitcnt lgkmcnt(1)
	v_mfma_f32_32x32x16_bf16 v[50:65], v[246:249], v[2:5], 0
	s_waitcnt lgkmcnt(0)
	v_mfma_f32_32x32x16_bf16 v[50:65], v[250:253], v[6:9], v[50:65]
	s_nop 11
	v_cvt_pk_bf16_f32 v2, v50, v51
	v_cvt_pk_bf16_f32 v3, v52, v53
	v_cvt_pk_bf16_f32 v4, v54, v55
	v_cvt_pk_bf16_f32 v5, v56, v57
	v_cvt_pk_bf16_f32 v6, v58, v59
	v_cvt_pk_bf16_f32 v7, v60, v61
	v_cvt_pk_bf16_f32 v8, v62, v63
	v_cvt_pk_bf16_f32 v9, v64, v65
	v_cvt_pk_bf16_f32 v10, v34, v35
	v_cvt_pk_bf16_f32 v11, v36, v37
	v_cvt_pk_bf16_f32 v12, v38, v39
	v_cvt_pk_bf16_f32 v13, v40, v41
	v_cvt_pk_bf16_f32 v14, v42, v43
	v_cvt_pk_bf16_f32 v15, v44, v45
	v_cvt_pk_bf16_f32 v16, v46, v47
	v_cvt_pk_bf16_f32 v17, v48, v49
	s_waitcnt lgkmcnt(2)
	v_mfma_f32_32x32x16_bf16 v[34:49], v[2:5], v[10:13], v[34:49]
	s_waitcnt lgkmcnt(0)
	v_mfma_f32_32x32x16_bf16 v[34:49], v[6:9], v[14:17], v[34:49]
	s_nop 11
	v_cvt_pk_bf16_f32 v34, v34, s0
	s_movk_i32 s0, 0x140
	v_mul_lo_u32 v50, v111, s0
	v_add3_u32 v50, s35, v176, v50
	ds_write_b16 v50, v34
	v_cvt_pk_bf16_f32 v34, v35, s0
	ds_write_b16 v50, v34 offset:80
	v_cvt_pk_bf16_f32 v34, v36, s0
	ds_write_b16 v50, v34 offset:160
	v_cvt_pk_bf16_f32 v34, v37, s0
	ds_write_b16 v50, v34 offset:240
	v_cvt_pk_bf16_f32 v34, v38, s0
	ds_write_b16 v50, v34 offset:640
	v_cvt_pk_bf16_f32 v34, v39, s0
	ds_write_b16 v50, v34 offset:720
	v_cvt_pk_bf16_f32 v34, v40, s0
	ds_write_b16 v50, v34 offset:800
	v_cvt_pk_bf16_f32 v34, v41, s0
	ds_write_b16 v50, v34 offset:880
	v_cvt_pk_bf16_f32 v34, v42, s0
	ds_write_b16 v50, v34 offset:1280
	v_cvt_pk_bf16_f32 v34, v43, s0
	ds_write_b16 v50, v34 offset:1360
	v_cvt_pk_bf16_f32 v34, v44, s0
	ds_write_b16 v50, v34 offset:1440
	v_cvt_pk_bf16_f32 v34, v45, s0
	ds_write_b16 v50, v34 offset:1520
	v_cvt_pk_bf16_f32 v34, v46, s0
	ds_write_b16 v50, v34 offset:1920
	v_cvt_pk_bf16_f32 v34, v47, s0
	ds_write_b16 v50, v34 offset:2000
	v_cvt_pk_bf16_f32 v34, v48, s0
	ds_write_b16 v50, v34 offset:2080
	v_cvt_pk_bf16_f32 v34, v49, s0
	ds_write_b16 v50, v34 offset:2160
	s_setprio 0
	s_and_b64 vcc, exec, s[52:53]
	v_or_b32_e32 v51, s81, v99
	v_mul_u32_u24_e32 v50, 0x50, v101
	s_cbranch_vccz .LBB0_774
	s_branch .LBB0_775
